# attention queues: a first wave of 52 light diff items, then (heavy, light) pairs, the shortest heavy items last
# speedup vs baseline: 1.0018x; 1.0018x over previous
.LBB0_840:
	s_andn2_b64 vcc, exec, s[38:39]
	s_cbranch_vccnz .LBB0_842
	s_add_i32 s4, s54, -12
	s_add_i32 s30, s4, -52
	s_lshr_b32 s31, s30, 1
	s_andn2_b32 s50, 0x7f, s31
	s_add_i32 s31, s31, 52
	s_bitcmp0_b32 s30, 0
	s_cselect_b32 s50, s50, s31
	s_cselect_b32 s31, 1, 0
	s_sub_i32 s30, 0xff, s4
	s_cmpk_lt_u32 s4, 0xcc
	s_cselect_b32 s50, s50, s30
	s_cselect_b32 s31, s31, 1
	s_cmpk_lt_u32 s4, 52
	s_cselect_b32 s50, s4, s50
	s_cselect_b32 s31, 0, s31
	s_cmp_eq_u32 s31, 1
	v_readlane_b32 s4, v250, 18
	v_readlane_b32 s5, v250, 19
	s_cselect_b32 s6, 2, 1
	s_cselect_b32 s30, 3, 0
	s_and_b64 s[4:5], s[4:5], exec
	s_cselect_b32 s6, s30, s6
	s_mov_b64 s[4:5], 0
	s_mov_b32 s55, s71
